# attention epilogue: 16 serial subln-gain loads (each with vmcnt(0) that also waited on the previous output store) hoisted into one batch at block entry
# speedup vs baseline: 1.0142x; 1.0042x over previous
.LBB0_617:
	v_readlane_b32 s2, v240, 26
	v_readlane_b32 s3, v240, 27
	s_andn2_b64 vcc, exec, s[2:3]
	s_waitcnt lgkmcnt(0)
	s_barrier
	s_cbranch_vccnz .LBB0_619
	global_load_dwordx4 v[0:3], v[142:143], off
	global_load_dwordx4 v[4:7], v[142:143], off offset:32
	global_load_dwordx4 v[8:11], v[142:143], off offset:64
	global_load_dwordx4 v[12:15], v[142:143], off offset:96
	global_load_dwordx4 v[16:19], v[142:143], off offset:128
	global_load_dwordx4 v[20:23], v[142:143], off offset:160
	global_load_dwordx4 v[24:27], v[142:143], off offset:192
	global_load_dwordx4 v[28:31], v[142:143], off offset:224
	global_load_dwordx4 v[32:35], v[142:143], off offset:256
	global_load_dwordx4 v[36:39], v[142:143], off offset:288
	global_load_dwordx4 v[40:43], v[142:143], off offset:320
	global_load_dwordx4 v[44:47], v[142:143], off offset:352
	global_load_dwordx4 v[48:51], v[142:143], off offset:384
	global_load_dwordx4 v[52:55], v[142:143], off offset:416
	global_load_dwordx4 v[56:59], v[142:143], off offset:448
	global_load_dwordx4 v[60:63], v[142:143], off offset:480
	ds_read2st64_b32 v[76:77], v174 offset1:1
	ds_read2st64_b32 v[78:79], v174 offset0:4 offset1:5
	ds_read2st64_b32 v[86:87], v174 offset0:8 offset1:9
	ds_read2st64_b32 v[108:109], v174 offset0:20 offset1:21
	v_readlane_b32 s2, v240, 11
	s_waitcnt lgkmcnt(3)
	v_sub_f32_e32 v75, v190, v76
	v_sub_f32_e32 v74, v224, v77
	ds_read2st64_b32 v[76:77], v174 offset0:2 offset1:3
	ds_read2st64_b32 v[82:83], v174 offset0:6 offset1:7
	ds_read2st64_b32 v[98:99], v174 offset0:12 offset1:13
	ds_read2st64_b32 v[118:119], v174 offset0:28 offset1:29
	s_waitcnt lgkmcnt(5)
	v_sub_f32_e32 v84, v217, v86
	ds_read2st64_b32 v[110:111], v174 offset0:26 offset1:27
	s_waitcnt lgkmcnt(3)
	v_sub_f32_e32 v81, v219, v82
	v_sub_f32_e32 v82, v218, v83
	v_sub_f32_e32 v83, v216, v87
	ds_read2st64_b32 v[86:87], v174 offset0:10 offset1:11
	s_waitcnt lgkmcnt(3)
	v_sub_f32_e32 v89, v213, v98
	s_waitcnt lgkmcnt(1)
	v_sub_f32_e32 v115, v199, v110
	v_sub_f32_e32 v113, v197, v118
	v_sub_f32_e32 v110, v195, v119
	s_waitcnt lgkmcnt(0)
	v_sub_f32_e32 v90, v215, v86
	v_sub_f32_e32 v86, v212, v99
	ds_read2st64_b32 v[98:99], v174 offset0:14 offset1:15
	ds_read2st64_b32 v[118:119], v174 offset0:30 offset1:31
	v_sub_f32_e32 v97, v204, v109
	ds_read2st64_b32 v[122:123], v174 offset0:34 offset1:35
	v_mul_f32_e32 v190, v74, v74
	s_waitcnt lgkmcnt(2)
	v_sub_f32_e32 v104, v211, v98
	v_sub_f32_e32 v101, v210, v99
	ds_read2st64_b32 v[98:99], v174 offset0:16 offset1:17
	s_waitcnt lgkmcnt(2)
	v_sub_f32_e32 v129, v129, v118
	v_sub_f32_e32 v126, v194, v119
	ds_read2st64_b32 v[118:119], v174 offset0:32 offset1:33
	s_waitcnt lgkmcnt(2)
	v_sub_f32_e32 v127, v191, v122
	s_waitcnt lgkmcnt(1)
	v_sub_f32_e32 v95, v209, v98
	v_sub_f32_e32 v93, v208, v99
	ds_read2st64_b32 v[98:99], v174 offset0:18 offset1:19
	s_waitcnt lgkmcnt(1)
	v_sub_f32_e32 v121, v193, v118
	v_sub_f32_e32 v119, v192, v119
	v_sub_f32_e32 v124, v189, v123
	ds_read2st64_b32 v[122:123], v174 offset0:36 offset1:37
	s_waitcnt lgkmcnt(1)
	v_sub_f32_e32 v102, v207, v98
	v_sub_f32_e32 v98, v206, v99
	v_sub_f32_e32 v99, v205, v108
	ds_read2st64_b32 v[108:109], v174 offset0:22 offset1:23
	ds_read2st64_b32 v[192:193], v174 offset0:38 offset1:39
	v_fmac_f32_e32 v190, v75, v75
	v_sub_f32_e32 v76, v223, v76
	v_fmac_f32_e32 v190, v76, v76
	s_waitcnt lgkmcnt(1)
	v_sub_f32_e32 v116, v203, v108
	v_sub_f32_e32 v114, v202, v109
	ds_read2st64_b32 v[108:109], v174 offset0:24 offset1:25
	v_sub_f32_e32 v77, v222, v77
	v_fmac_f32_e32 v190, v77, v77
	v_sub_f32_e32 v78, v221, v78
	v_sub_f32_e32 v125, v188, v122
	s_waitcnt lgkmcnt(1)
	v_sub_f32_e32 v189, v152, v192
	v_sub_f32_e32 v188, v151, v193
	ds_read2st64_b32 v[192:193], v174 offset0:40 offset1:41
	v_fmac_f32_e32 v190, v78, v78
	v_sub_f32_e32 v79, v220, v79
	v_fmac_f32_e32 v190, v79, v79
	v_fmac_f32_e32 v190, v81, v81
	v_fmac_f32_e32 v190, v82, v82
	v_fmac_f32_e32 v190, v84, v84
	v_sub_f32_e32 v123, v153, v123
	s_waitcnt lgkmcnt(0)
	v_sub_f32_e32 v153, v149, v192
	v_sub_f32_e32 v152, v145, v193
	ds_read2st64_b32 v[192:193], v174 offset0:42 offset1:43
	v_fmac_f32_e32 v190, v83, v83
	v_fmac_f32_e32 v190, v90, v90
	v_sub_f32_e32 v87, v214, v87
	v_fmac_f32_e32 v190, v87, v87
	v_fmac_f32_e32 v190, v89, v89
	v_fmac_f32_e32 v190, v86, v86
	s_waitcnt lgkmcnt(0)
	v_sub_f32_e32 v151, v130, v192
	v_sub_f32_e32 v130, v107, v193
	ds_read2st64_b32 v[192:193], v174 offset0:44 offset1:45
	v_fmac_f32_e32 v190, v104, v104
	v_fmac_f32_e32 v190, v101, v101
	v_fmac_f32_e32 v190, v95, v95
	v_fmac_f32_e32 v190, v93, v93
	v_fmac_f32_e32 v190, v102, v102
	s_waitcnt lgkmcnt(0)
	v_sub_f32_e32 v122, v105, v192
	v_sub_f32_e32 v120, v103, v193
	ds_read2st64_b32 v[192:193], v174 offset0:46 offset1:47
	v_fmac_f32_e32 v190, v98, v98
	v_fmac_f32_e32 v190, v99, v99
	v_fmac_f32_e32 v190, v97, v97
	v_fmac_f32_e32 v190, v116, v116
	v_fmac_f32_e32 v190, v114, v114
	v_sub_f32_e32 v108, v201, v108
	s_waitcnt lgkmcnt(0)
	v_sub_f32_e32 v118, v100, v192
	v_sub_f32_e32 v117, v96, v193
	ds_read2st64_b32 v[192:193], v174 offset0:48 offset1:49
	v_fmac_f32_e32 v190, v108, v108
	v_sub_f32_e32 v106, v200, v109
	v_fmac_f32_e32 v190, v106, v106
	v_fmac_f32_e32 v190, v115, v115
	v_sub_f32_e32 v111, v198, v111
	v_fmac_f32_e32 v190, v111, v111
	v_fmac_f32_e32 v190, v113, v113
	s_waitcnt lgkmcnt(0)
	v_sub_f32_e32 v112, v94, v192
	v_sub_f32_e32 v109, v92, v193
	ds_read2st64_b32 v[192:193], v174 offset0:50 offset1:51
	v_fmac_f32_e32 v190, v110, v110
	v_fmac_f32_e32 v190, v129, v129
	v_fmac_f32_e32 v190, v126, v126
	v_fmac_f32_e32 v190, v121, v121
	v_fmac_f32_e32 v190, v119, v119
	s_waitcnt lgkmcnt(0)
	v_sub_f32_e32 v107, v91, v192
	v_sub_f32_e32 v105, v88, v193
	ds_read2st64_b32 v[192:193], v174 offset0:52 offset1:53
	v_fmac_f32_e32 v190, v127, v127
	v_fmac_f32_e32 v190, v124, v124
	v_fmac_f32_e32 v190, v125, v125
	v_fmac_f32_e32 v190, v123, v123
	v_fmac_f32_e32 v190, v189, v189
	s_waitcnt lgkmcnt(0)
	v_sub_f32_e32 v103, v85, v192
	v_sub_f32_e32 v100, v80, v193
	ds_read2st64_b32 v[192:193], v174 offset0:54 offset1:55
	v_fmac_f32_e32 v190, v188, v188
	v_fmac_f32_e32 v190, v153, v153
	v_fmac_f32_e32 v190, v152, v152
	v_fmac_f32_e32 v190, v151, v151
	v_fmac_f32_e32 v190, v130, v130
	s_waitcnt lgkmcnt(0)
	v_sub_f32_e32 v96, v73, v192
	v_sub_f32_e32 v94, v72, v193
	ds_read2st64_b32 v[72:73], v174 offset0:56 offset1:57
	v_fmac_f32_e32 v190, v122, v122
	v_fmac_f32_e32 v190, v120, v120
	v_fmac_f32_e32 v190, v118, v118
	v_fmac_f32_e32 v190, v117, v117
	v_fmac_f32_e32 v190, v112, v112
	s_waitcnt lgkmcnt(0)
	v_sub_f32_e32 v92, v71, v72
	v_sub_f32_e32 v91, v70, v73
	ds_read2st64_b32 v[70:71], v174 offset0:58 offset1:59
	v_fmac_f32_e32 v190, v109, v109
	v_fmac_f32_e32 v190, v107, v107
	v_fmac_f32_e32 v190, v105, v105
	v_fmac_f32_e32 v190, v103, v103
	v_fmac_f32_e32 v190, v100, v100
	s_waitcnt lgkmcnt(0)
	v_sub_f32_e32 v88, v69, v70
	v_sub_f32_e32 v85, v68, v71
	ds_read2st64_b32 v[68:69], v174 offset0:60 offset1:61
	v_fmac_f32_e32 v190, v96, v96
	v_fmac_f32_e32 v190, v94, v94
	v_fmac_f32_e32 v190, v92, v92
	v_fmac_f32_e32 v190, v91, v91
	v_fmac_f32_e32 v190, v88, v88
	s_waitcnt lgkmcnt(0)
	v_pk_add_f32 v[72:73], v[64:65], v[68:69] neg_lo:[0,1] neg_hi:[0,1]
	v_fmac_f32_e32 v190, v85, v85
	v_pk_mul_f32 v[64:65], v[72:73], v[72:73]
	v_mov_b32_e32 v149, v131
	v_add_f32_e32 v64, v190, v64
	v_add_f32_e32 v68, v64, v65
	ds_read2st64_b32 v[64:65], v174 offset0:62 offset1:63
	v_readlane_b32 s3, v240, 12
	s_mov_b32 s81, s21
	v_mov_b32_e32 v145, v131
	s_waitcnt lgkmcnt(0)
	v_pk_add_f32 v[70:71], v[66:67], v[64:65] neg_lo:[0,1] neg_hi:[0,1]
	s_nop 0
	v_pk_mul_f32 v[64:65], v[70:71], v[70:71]
	s_nop 0
	v_add_f32_e32 v64, v68, v64
	v_add_f32_e32 v64, v64, v65
	ds_bpermute_b32 v65, v159, v64
	s_waitcnt lgkmcnt(0)
	v_add_f32_e32 v64, v64, v65
	v_fmamk_f32 v64, v64, 0x3c000000, v183
	v_rsq_f32_e32 v64, v64
	s_nop 0
	v_mul_f32_e32 v80, 0x3f4ccccd, v64
	v_lshlrev_b64 v[64:65], 12, v[148:149]
	v_lshl_add_u64 v[64:65], s[2:3], 0, v[64:65]
	v_lshl_add_u64 v[64:65], v[64:65], 0, s[80:81]
	v_lshl_add_u64 v[68:69], v[64:65], 0, v[144:145]
	v_mul_f32_e32 v75, v75, v80
	v_mul_f32_e32 v74, v74, v80
	v_mul_f32_e32 v72, v72, v80
	s_waitcnt vmcnt(0)
	v_mov_b32_e32 v64, v0
	v_mov_b32_e32 v65, v1
	v_mov_b32_e32 v66, v2
	v_mov_b32_e32 v67, v3
	v_mul_f32_e32 v64, v64, v75
	v_mul_f32_e32 v65, v65, v74
	v_cvt_pk_bf16_f32 v64, v64, v65
	v_mul_f32_e32 v65, v76, v80
	v_mul_f32_e32 v65, v66, v65
	v_mul_f32_e32 v66, v77, v80
	v_mul_f32_e32 v66, v67, v66
	v_cvt_pk_bf16_f32 v65, v65, v66
	global_store_dwordx2 v[68:69], v[64:65], off offset:2048
	v_mul_f32_e32 v74, v78, v80
	v_mov_b32_e32 v64, v4
	v_mov_b32_e32 v65, v5
	v_mov_b32_e32 v66, v6
	v_mov_b32_e32 v67, v7
	v_mul_f32_e32 v64, v64, v74
	v_mul_f32_e32 v74, v79, v80
	v_mul_f32_e32 v65, v65, v74
	v_cvt_pk_bf16_f32 v64, v64, v65
	v_mul_f32_e32 v65, v81, v80
	v_mul_f32_e32 v65, v66, v65
	v_mul_f32_e32 v66, v82, v80
	v_mul_f32_e32 v66, v67, v66
	v_cvt_pk_bf16_f32 v65, v65, v66
	global_store_dwordx2 v[68:69], v[64:65], off offset:2064
	v_mul_f32_e32 v74, v84, v80
	v_mov_b32_e32 v64, v8
	v_mov_b32_e32 v65, v9
	v_mov_b32_e32 v66, v10
	v_mov_b32_e32 v67, v11
	v_mul_f32_e32 v64, v74, v64
	v_mul_f32_e32 v74, v83, v80
	v_mul_f32_e32 v65, v74, v65
	v_cvt_pk_bf16_f32 v64, v64, v65
	v_mul_f32_e32 v65, v90, v80
	v_mul_f32_e32 v65, v65, v66
	v_mul_f32_e32 v66, v87, v80
	v_mul_f32_e32 v66, v66, v67
	v_cvt_pk_bf16_f32 v65, v65, v66
	global_store_dwordx2 v[68:69], v[64:65], off offset:2080
	v_mul_f32_e32 v74, v89, v80
	v_mov_b32_e32 v64, v12
	v_mov_b32_e32 v65, v13
	v_mov_b32_e32 v66, v14
	v_mov_b32_e32 v67, v15
	v_mul_f32_e32 v64, v74, v64
	v_mul_f32_e32 v74, v86, v80
	v_mul_f32_e32 v65, v74, v65
	v_cvt_pk_bf16_f32 v64, v64, v65
	v_mul_f32_e32 v65, v104, v80
	v_mul_f32_e32 v65, v65, v66
	v_mul_f32_e32 v66, v101, v80
	v_mul_f32_e32 v66, v66, v67
	v_cvt_pk_bf16_f32 v65, v65, v66
	global_store_dwordx2 v[68:69], v[64:65], off offset:2096
	v_mul_f32_e32 v74, v95, v80
	v_mov_b32_e32 v64, v16
	v_mov_b32_e32 v65, v17
	v_mov_b32_e32 v66, v18
	v_mov_b32_e32 v67, v19
	v_mul_f32_e32 v64, v74, v64
	v_mul_f32_e32 v74, v93, v80
	v_mul_f32_e32 v65, v74, v65
	v_cvt_pk_bf16_f32 v64, v64, v65
	v_mul_f32_e32 v65, v102, v80
	v_mul_f32_e32 v65, v65, v66
	v_mul_f32_e32 v66, v98, v80
	v_mul_f32_e32 v66, v66, v67
	v_cvt_pk_bf16_f32 v65, v65, v66
	global_store_dwordx2 v[68:69], v[64:65], off offset:2112
	v_mul_f32_e32 v74, v99, v80
	v_mov_b32_e32 v64, v20
	v_mov_b32_e32 v65, v21
	v_mov_b32_e32 v66, v22
	v_mov_b32_e32 v67, v23
	v_mul_f32_e32 v64, v74, v64
	v_mul_f32_e32 v74, v97, v80
	v_mul_f32_e32 v65, v74, v65
	v_cvt_pk_bf16_f32 v64, v64, v65
	v_mul_f32_e32 v65, v116, v80
	v_mul_f32_e32 v65, v65, v66
	v_mul_f32_e32 v66, v114, v80
	v_mul_f32_e32 v66, v66, v67
	v_cvt_pk_bf16_f32 v65, v65, v66
	global_store_dwordx2 v[68:69], v[64:65], off offset:2128
	v_mul_f32_e32 v74, v108, v80
	v_mov_b32_e32 v64, v24
	v_mov_b32_e32 v65, v25
	v_mov_b32_e32 v66, v26
	v_mov_b32_e32 v67, v27
	v_mul_f32_e32 v64, v74, v64
	v_mul_f32_e32 v74, v106, v80
	v_mul_f32_e32 v65, v74, v65
	v_cvt_pk_bf16_f32 v64, v64, v65
	v_mul_f32_e32 v65, v115, v80
	v_mul_f32_e32 v65, v65, v66
	v_mul_f32_e32 v66, v111, v80
	v_mul_f32_e32 v66, v66, v67
	v_cvt_pk_bf16_f32 v65, v65, v66
	global_store_dwordx2 v[68:69], v[64:65], off offset:2144
	v_mul_f32_e32 v74, v113, v80
	v_mov_b32_e32 v64, v28
	v_mov_b32_e32 v65, v29
	v_mov_b32_e32 v66, v30
	v_mov_b32_e32 v67, v31
	v_mul_f32_e32 v64, v74, v64
	v_mul_f32_e32 v74, v110, v80
	v_mul_f32_e32 v65, v74, v65
	v_cvt_pk_bf16_f32 v64, v64, v65
	v_mul_f32_e32 v65, v129, v80
	v_mul_f32_e32 v65, v65, v66
	v_mul_f32_e32 v66, v126, v80
	v_mul_f32_e32 v66, v66, v67
	v_cvt_pk_bf16_f32 v65, v65, v66
	global_store_dwordx2 v[68:69], v[64:65], off offset:2160
	v_mul_f32_e32 v74, v121, v80
	v_mov_b32_e32 v64, v32
	v_mov_b32_e32 v65, v33
	v_mov_b32_e32 v66, v34
	v_mov_b32_e32 v67, v35
	v_mul_f32_e32 v64, v74, v64
	v_mul_f32_e32 v74, v119, v80
	v_mul_f32_e32 v65, v74, v65
	v_cvt_pk_bf16_f32 v64, v64, v65
	v_mul_f32_e32 v65, v127, v80
	v_mul_f32_e32 v65, v65, v66
	v_mul_f32_e32 v66, v124, v80
	v_mul_f32_e32 v66, v66, v67
	v_cvt_pk_bf16_f32 v65, v65, v66
	global_store_dwordx2 v[68:69], v[64:65], off offset:2176
	v_mul_f32_e32 v74, v125, v80
	v_mov_b32_e32 v64, v36
	v_mov_b32_e32 v65, v37
	v_mov_b32_e32 v66, v38
	v_mov_b32_e32 v67, v39
	v_mul_f32_e32 v64, v74, v64
	v_mul_f32_e32 v74, v123, v80
	v_mul_f32_e32 v65, v74, v65
	v_cvt_pk_bf16_f32 v64, v64, v65
	v_mul_f32_e32 v65, v189, v80
	v_mul_f32_e32 v65, v65, v66
	v_mul_f32_e32 v66, v188, v80
	v_mul_f32_e32 v66, v66, v67
	v_cvt_pk_bf16_f32 v65, v65, v66
	global_store_dwordx2 v[68:69], v[64:65], off offset:2192
	v_mul_f32_e32 v74, v153, v80
	v_mov_b32_e32 v64, v40
	v_mov_b32_e32 v65, v41
	v_mov_b32_e32 v66, v42
	v_mov_b32_e32 v67, v43
	v_mul_f32_e32 v64, v74, v64
	v_mul_f32_e32 v74, v152, v80
	v_mul_f32_e32 v65, v74, v65
	v_cvt_pk_bf16_f32 v64, v64, v65
	v_mul_f32_e32 v65, v151, v80
	v_mul_f32_e32 v65, v65, v66
	v_mul_f32_e32 v66, v130, v80
	v_mul_f32_e32 v66, v66, v67
	v_cvt_pk_bf16_f32 v65, v65, v66
	global_store_dwordx2 v[68:69], v[64:65], off offset:2208
	v_mul_f32_e32 v74, v122, v80
	v_mov_b32_e32 v64, v44
	v_mov_b32_e32 v65, v45
	v_mov_b32_e32 v66, v46
	v_mov_b32_e32 v67, v47
	v_mul_f32_e32 v64, v74, v64
	v_mul_f32_e32 v74, v120, v80
	v_mul_f32_e32 v65, v74, v65
	v_cvt_pk_bf16_f32 v64, v64, v65
	v_mul_f32_e32 v65, v118, v80
	v_mul_f32_e32 v65, v65, v66
	v_mul_f32_e32 v66, v117, v80
	v_mul_f32_e32 v66, v66, v67
	v_cvt_pk_bf16_f32 v65, v65, v66
	global_store_dwordx2 v[68:69], v[64:65], off offset:2224
	v_mul_f32_e32 v74, v112, v80
	v_mov_b32_e32 v64, v48
	v_mov_b32_e32 v65, v49
	v_mov_b32_e32 v66, v50
	v_mov_b32_e32 v67, v51
	v_mul_f32_e32 v64, v74, v64
	v_mul_f32_e32 v74, v109, v80
	v_mul_f32_e32 v65, v74, v65
	v_cvt_pk_bf16_f32 v64, v64, v65
	v_mul_f32_e32 v65, v107, v80
	v_mul_f32_e32 v65, v65, v66
	v_mul_f32_e32 v66, v105, v80
	v_mul_f32_e32 v66, v66, v67
	v_cvt_pk_bf16_f32 v65, v65, v66
	global_store_dwordx2 v[68:69], v[64:65], off offset:2240
	v_mul_f32_e32 v74, v103, v80
	v_mov_b32_e32 v64, v52
	v_mov_b32_e32 v65, v53
	v_mov_b32_e32 v66, v54
	v_mov_b32_e32 v67, v55
	v_mul_f32_e32 v64, v74, v64
	v_mul_f32_e32 v74, v100, v80
	v_mul_f32_e32 v65, v74, v65
	v_cvt_pk_bf16_f32 v64, v64, v65
	v_mul_f32_e32 v65, v96, v80
	v_mul_f32_e32 v65, v65, v66
	v_mul_f32_e32 v66, v94, v80
	v_mul_f32_e32 v66, v66, v67
	v_cvt_pk_bf16_f32 v65, v65, v66
	global_store_dwordx2 v[68:69], v[64:65], off offset:2256
	v_mul_f32_e32 v74, v92, v80
	v_mov_b32_e32 v64, v56
	v_mov_b32_e32 v65, v57
	v_mov_b32_e32 v66, v58
	v_mov_b32_e32 v67, v59
	v_mul_f32_e32 v64, v74, v64
	v_mul_f32_e32 v74, v91, v80
	v_mul_f32_e32 v65, v74, v65
	v_cvt_pk_bf16_f32 v64, v64, v65
	v_mul_f32_e32 v65, v88, v80
	v_mul_f32_e32 v65, v65, v66
	v_mul_f32_e32 v66, v85, v80
	v_mul_f32_e32 v66, v66, v67
	v_cvt_pk_bf16_f32 v65, v65, v66
	global_store_dwordx2 v[68:69], v[64:65], off offset:2272
	v_mov_b32_e32 v64, v60
	v_mov_b32_e32 v65, v61
	v_mov_b32_e32 v66, v62
	v_mov_b32_e32 v67, v63
	v_mul_f32_e32 v64, v72, v64
	v_mul_f32_e32 v72, v73, v80
	v_mul_f32_e32 v65, v72, v65
	v_cvt_pk_bf16_f32 v64, v64, v65
	v_mul_f32_e32 v65, v70, v80
	v_mul_f32_e32 v65, v65, v66
	v_mul_f32_e32 v66, v71, v80
	v_mul_f32_e32 v66, v66, v67
	v_cvt_pk_bf16_f32 v65, v65, v66
	global_store_dwordx2 v[68:69], v[64:65], off offset:2288
